# P0 role split: workgroups with blockIdx bit 3 set stream their XN rows before their weight-transpose items
# speedup vs baseline: 1.0018x; 1.0018x over previous
.LBB0_9:
	s_or_b64 exec, exec, s[8:9]
	s_lshl_b32 s33, s34, 3
	s_lshr_b32 s71, s3, 6
	s_add_u32 s62, s30, 0x4000000
	s_addc_u32 s63, s31, 0
	s_load_dwordx16 s[12:27], s[0:1], 0x40
	s_cmp_lt_i32 s60, 1
	s_cselect_b64 s[0:1], -1, 0
	s_cmp_gt_i32 s61, 0
	s_cselect_b64 s[8:9], -1, 0
	s_and_b64 s[8:9], s[0:1], s[8:9]
	s_andn2_b64 vcc, exec, s[8:9]
	s_cbranch_vccnz .LBB0_119
	v_readlane_b32 s0, v254, 8
	s_lshl_b32 s0, s0, 3
	v_mbcnt_hi_u32_b32 v75, -1, v228
	s_add_i32 s10, s71, s0
	s_mov_b32 s69, 0
	v_mov_b32_e32 v18, v75
	s_mov_b32 s98, 0
	s_cmpk_gt_i32 s10, 0x28ff
	s_cbranch_scc1 .LBB0_109
	s_bitcmp1_b32 s2, 3
	s_cbranch_scc0 .Lp0_items
	s_waitcnt lgkmcnt(0)
	v_writelane_b32 v254, s10, 20
	v_writelane_b32 v254, s24, 21
	v_writelane_b32 v254, s25, 22
	v_writelane_b32 v254, s26, 23
	v_writelane_b32 v254, s27, 24
	v_writelane_b32 v254, s42, 25
	v_writelane_b32 v254, s43, 26
	v_writelane_b32 v254, s44, 27
	v_writelane_b32 v254, s45, 28
	v_writelane_b32 v254, s46, 29
	v_writelane_b32 v254, s47, 30
	v_writelane_b32 v254, s48, 31
	v_writelane_b32 v254, s49, 32
	s_mov_b32 s98, 1
	s_branch .LBB0_109
.Lp0_items:
	v_lshlrev_b32_e32 v1, 2, v18
	v_and_b32_e32 v42, 0x7c, v1
	v_lshlrev_b32_e32 v1, 3, v18
	v_and_b32_e32 v1, 56, v1
	v_lshlrev_b32_e32 v20, 1, v1
	v_mov_b32_e32 v21, 0
	v_lshl_add_u64 v[16:17], s[30:31], 0, v[20:21]
	s_mov_b64 s[0:1], 0x1800000
	v_lshl_add_u64 v[6:7], v[16:17], 0, s[0:1]
	s_mov_b64 s[0:1], 0x1200000
	s_lshl_b32 s52, s71, 14
	v_lshl_add_u64 v[8:9], v[16:17], 0, s[0:1]
	s_mov_b64 s[0:1], 0x2500000
	s_add_i32 s53, s52, 0
	v_ashrrev_i32_e32 v2, 5, v18
	s_movk_i32 s11, 0x84
	v_lshl_add_u64 v[10:11], v[16:17], 0, s[0:1]
	s_mov_b64 s[0:1], 0x1a00000
	v_ashrrev_i32_e32 v76, 3, v18
	v_lshl_add_u64 v[12:13], v[16:17], 0, s[0:1]
	s_mov_b64 s[0:1], 0xc00000
	v_mov_b32_e32 v43, v21
	v_readlane_b32 s72, v254, 0
	s_cmp_lg_u64 s[48:49], 0
	v_mul_lo_u32 v31, v2, s11
	v_mul_u32_u24_e32 v3, 0x84, v1
	v_lshlrev_b32_e32 v1, 2, v76
	v_lshl_add_u64 v[14:15], v[16:17], 0, s[0:1]
	s_mov_b64 s[0:1], 0x100000
	s_waitcnt lgkmcnt(0)
	v_lshl_add_u64 v[20:21], s[24:25], 0, v[42:43]
	v_readlane_b32 s73, v254, 1
	v_readlane_b32 s74, v254, 2
	v_readlane_b32 s75, v254, 3
	v_readlane_b32 s76, v254, 4
	v_readlane_b32 s77, v254, 5
	s_cselect_b64 s[24:25], -1, 0
	s_cmp_lg_u64 s[26:27], 0
	v_add_u32_e32 v30, 4, v2
	v_add_u32_e32 v32, 8, v2
	v_add_u32_e32 v34, 12, v2
	v_ashrrev_i32_e32 v39, 31, v2
	v_mov_b32_e32 v38, v2
	v_add_u32_e32 v31, s52, v31
	v_add_u32_e32 v44, 16, v2
	v_add_u32_e32 v46, 20, v2
	v_add_u32_e32 v48, 24, v2
	v_add_u32_e32 v50, 28, v2
	v_add_u32_e32 v4, s53, v42
	v_add3_u32 v77, s53, v3, v1
	v_add_u32_e32 v78, 8, v76
	v_add_u32_e32 v79, 16, v76
	v_add_u32_e32 v80, 24, v76
	v_lshl_add_u64 v[16:17], v[16:17], 0, s[0:1]
	v_lshl_add_u64 v[22:23], s[76:77], 0, v[42:43]
	v_lshl_add_u64 v[24:25], s[46:47], 0, v[42:43]
	v_lshl_add_u64 v[26:27], s[44:45], 0, v[42:43]
	v_lshl_add_u64 v[28:29], s[42:43], 0, v[42:43]
	s_cselect_b64 s[42:43], -1, 0
	v_mov_b32_e32 v1, v2
	v_mov_b32_e32 v3, v30
	v_mov_b32_e32 v5, v32
	v_mov_b32_e32 v19, v34
	v_add3_u32 v81, v31, v42, 0
	v_lshl_add_u64 v[36:37], s[50:51], 0, v[42:43]
	v_add_u32_e32 v82, 14, v2
	v_lshlrev_b64 v[38:39], 2, v[38:39]
	v_add_u32_e32 v83, 10, v2
	v_add_u32_e32 v84, 6, v2
	v_add_u32_e32 v85, 2, v2
	v_lshl_add_u64 v[40:41], s[74:75], 0, v[42:43]
	v_lshl_add_u64 v[42:43], s[72:73], 0, v[42:43]
	s_movk_i32 s45, 0x880
	s_movk_i32 s47, 0x3000
	s_movk_i32 s54, 0x1600
	s_movk_i32 s55, 0x2c00
	s_mov_b32 s44, 0x3f317218
	s_mov_b32 s46, 0x3fb8aa3b
	s_mov_b32 s56, s10
	v_mov_b32_e32 v31, v44
	v_mov_b32_e32 v33, v46
	v_mov_b32_e32 v35, v48
	v_mov_b32_e32 v45, v50
	v_readlane_b32 s78, v254, 6
	v_readlane_b32 s79, v254, 7
	s_branch .LBB0_13

.LBB0_109:
	s_cmp_eq_u32 s98, 2
	s_cbranch_scc1 .Lp0_end
	s_cmp_lt_i32 s10, 0x14000
	s_cbranch_scc0 .LBB0_118
	v_ashrrev_i32_e32 v19, 31, v18
	v_lshl_add_u64 v[20:21], v[18:19], 4, s[40:41]
	global_load_dwordx4 v[2:5], v[20:21], off
	global_load_dwordx4 v[6:9], v[20:21], off offset:1024
	global_load_dwordx4 v[10:13], v[20:21], off offset:2048
	global_load_dwordx4 v[14:17], v[20:21], off offset:3072
	v_and_b32_e32 v1, 64, v75
	v_add_u32_e32 v20, 64, v1
	v_xor_b32_e32 v1, 1, v75
	v_cmp_lt_i32_e32 vcc, v1, v20
	v_xor_b32_e32 v21, 2, v75
	s_add_u32 s46, s30, 0x3800000
	v_cndmask_b32_e32 v1, v75, v1, vcc
	v_cmp_lt_i32_e32 vcc, v21, v20
	v_lshl_add_u64 v[50:51], v[18:19], 3, s[62:63]
	v_lshlrev_b32_e32 v1, 2, v1
	v_cndmask_b32_e32 v21, v75, v21, vcc
	v_lshlrev_b32_e32 v55, 2, v21
	v_xor_b32_e32 v21, 4, v75
	v_cmp_lt_i32_e32 vcc, v21, v20
	s_waitcnt lgkmcnt(0)
	s_mov_b32 s25, 0
	v_cmp_eq_u32_e64 s[0:1], 0, v18
	v_cndmask_b32_e32 v21, v75, v21, vcc
	v_lshlrev_b32_e32 v57, 2, v21
	v_xor_b32_e32 v21, 8, v75
	v_cmp_lt_i32_e32 vcc, v21, v20
	s_addc_u32 s47, s31, 0
	v_lshlrev_b64 v[52:53], 4, v[18:19]
	v_cndmask_b32_e32 v21, v75, v21, vcc
	v_lshlrev_b32_e32 v58, 2, v21
	v_xor_b32_e32 v21, 16, v75
	v_cmp_lt_i32_e32 vcc, v21, v20
	v_mov_b32_e32 v61, 0x358637bd
	v_mov_b32_e32 v62, 0
	v_cndmask_b32_e32 v21, v75, v21, vcc
	v_lshlrev_b32_e32 v59, 2, v21
	v_xor_b32_e32 v21, 32, v75
	v_cmp_lt_i32_e32 vcc, v21, v20
	s_nop 1
	v_cndmask_b32_e32 v20, v75, v21, vcc
	v_lshlrev_b32_e32 v60, 2, v20
	s_branch .LBB0_112

.LBB0_118:
	s_cmp_eq_u32 s98, 1
	s_cbranch_scc0 .Lp0_end
	v_readlane_b32 s10, v254, 20
	v_readlane_b32 s24, v254, 21
	v_readlane_b32 s25, v254, 22
	v_readlane_b32 s26, v254, 23
	v_readlane_b32 s27, v254, 24
	v_readlane_b32 s42, v254, 25
	v_readlane_b32 s43, v254, 26
	v_readlane_b32 s44, v254, 27
	v_readlane_b32 s45, v254, 28
	v_readlane_b32 s46, v254, 29
	v_readlane_b32 s47, v254, 30
	v_readlane_b32 s48, v254, 31
	v_readlane_b32 s49, v254, 32
	v_mov_b32_e32 v18, v75
	s_mov_b32 s98, 2
	s_nop 4
	s_branch .Lp0_items
